# P7 tile order: column tile rotated by 2 per round so every workgroup gets two tiles of each kind instead of 8 workgroups per XCD doing all the log-gate (fp32, transcendental-heavy) tiles
# speedup vs baseline: 1.0059x; 1.0059x over previous
.LBB0_788:
	s_ashr_i32 s0, s21, 31
	s_lshr_b32 s0, s0, 28
	s_add_i32 s0, s21, s0
	s_ashr_i32 s1, s0, 4
	s_add_i32 s11, s1, s56
	s_lshl_b32 s11, s11, 8
	v_add_u32_e32 v4, s11, v163
	v_ashrrev_i32_e32 v5, 31, v4
	s_and_b32 s0, s0, -16
	v_lshlrev_b64 v[4:5], 11, v[4:5]
	s_sub_i32 s10, s21, s0
	s_lshr_b32 s0, s21, 5
	s_lshl_b32 s0, s0, 1
	s_add_i32 s10, s10, s0
	s_and_b32 s10, s10, 15
	v_lshl_add_u64 v[6:7], s[28:29], 0, v[4:5]
	v_readfirstlane_b32 s0, v165
	v_lshl_add_u64 v[6:7], v[6:7], 0, v[138:139]
	s_mov_b32 m0, s0
	s_barrier
	global_load_lds_dwordx4 v[6:7], off
	v_add_u32_e32 v6, s11, v164
	s_lshl_b32 s22, s10, 8
	v_ashrrev_i32_e32 v7, 31, v6
	v_add_u32_e32 v0, s22, v163
	v_lshlrev_b64 v[6:7], 11, v[6:7]
	v_ashrrev_i32_e32 v1, 31, v0
	v_add_u32_e32 v2, s22, v164
	v_lshl_add_u64 v[8:9], s[28:29], 0, v[6:7]
	v_readfirstlane_b32 s0, v183
	v_lshlrev_b64 v[0:1], 11, v[0:1]
	v_ashrrev_i32_e32 v3, 31, v2
	v_lshl_add_u64 v[8:9], v[8:9], 0, v[138:139]
	s_mov_b32 m0, s0
	v_readfirstlane_b32 s0, v184
	v_lshl_add_u64 v[0:1], v[130:131], 0, v[0:1]
	v_lshlrev_b64 v[2:3], 11, v[2:3]
	global_load_lds_dwordx4 v[8:9], off
	s_mov_b32 m0, s0
	v_readfirstlane_b32 s0, v185
	v_lshl_add_u64 v[2:3], v[130:131], 0, v[2:3]
	global_load_lds_dwordx4 v[0:1], off
	s_mov_b32 m0, s0
	v_lshl_add_u64 v[8:9], v[132:133], 0, v[4:5]
	v_readfirstlane_b32 s0, v186
	global_load_lds_dwordx4 v[2:3], off
	v_lshl_add_u64 v[10:11], v[8:9], 0, s[4:5]
	s_mov_b32 m0, s0
	v_readfirstlane_b32 s0, v187
	global_load_lds_dwordx4 v[10:11], off
	v_lshl_add_u64 v[10:11], v[132:133], 0, v[6:7]
	v_lshl_add_u64 v[12:13], v[10:11], 0, s[4:5]
	s_mov_b32 m0, s0
	v_readfirstlane_b32 s0, v188
	global_load_lds_dwordx4 v[12:13], off
	v_lshl_add_u64 v[12:13], v[0:1], 0, 64
	s_mov_b32 m0, s0
	v_readfirstlane_b32 s0, v189
	global_load_lds_dwordx4 v[12:13], off
	v_lshl_add_u64 v[12:13], v[2:3], 0, 64
	s_mov_b32 m0, s0
	v_readfirstlane_b32 s0, v190
	global_load_lds_dwordx4 v[12:13], off
	v_lshl_add_u64 v[8:9], v[8:9], 0, s[6:7]
	s_mov_b32 m0, s0
	v_readfirstlane_b32 s0, v192
	global_load_lds_dwordx4 v[8:9], off
	v_lshl_add_u64 v[8:9], v[10:11], 0, s[6:7]
	s_mov_b32 m0, s0
	v_readfirstlane_b32 s0, v194
	global_load_lds_dwordx4 v[8:9], off
	v_lshl_add_u64 v[0:1], v[0:1], 0, s[8:9]
	s_mov_b32 m0, s0
	v_readfirstlane_b32 s0, v196
	global_load_lds_dwordx4 v[0:1], off
	v_lshl_add_u64 v[0:1], v[2:3], 0, s[8:9]
	s_mov_b32 m0, s0
	s_mov_b32 s0, s22
	global_load_lds_dwordx4 v[0:1], off
	v_add_u32_e32 v0, s0, v163
	s_mov_b32 s1, 0
	v_subrev_u32_e32 v0, s1, v0
	v_ashrrev_i32_e32 v1, 31, v0
	v_lshlrev_b64 v[0:1], 11, v[0:1]
	v_lshl_add_u64 v[140:141], v[134:135], 0, v[0:1]
	v_add_u32_e32 v0, s0, v164
	v_subrev_u32_e32 v0, s1, v0
	v_ashrrev_i32_e32 v1, 31, v0
	v_lshlrev_b64 v[0:1], 11, v[0:1]
	v_lshl_add_u64 v[142:143], v[134:135], 0, v[0:1]
	v_lshl_add_u64 v[144:145], v[136:137], 0, v[4:5]
	v_lshl_add_u64 v[146:147], v[136:137], 0, v[6:7]
	s_mov_b64 s[0:1], 0
	s_mov_b32 s12, 0x18000
	v_mov_b32_e32 v0, 0
	v_mov_b32_e32 v1, v129
	v_mov_b32_e32 v2, v129
	v_mov_b32_e32 v3, v129
	v_mov_b32_e32 v4, v129
	v_mov_b32_e32 v5, v129
	v_mov_b32_e32 v6, v129
	v_mov_b32_e32 v7, v129
	v_mov_b32_e32 v8, v129
	v_mov_b32_e32 v9, v129
	v_mov_b32_e32 v10, v129
	v_mov_b32_e32 v11, v129
	v_mov_b32_e32 v12, v129
	v_mov_b32_e32 v13, v129
	v_mov_b32_e32 v14, v129
	v_mov_b32_e32 v15, v129
	v_mov_b32_e32 v16, 0
	v_mov_b32_e32 v17, v129
	v_mov_b32_e32 v18, v129
	v_mov_b32_e32 v19, v129
	v_mov_b32_e32 v20, v129
	v_mov_b32_e32 v21, v129
	v_mov_b32_e32 v22, v129
	v_mov_b32_e32 v23, v129
	v_mov_b32_e32 v24, v129
	v_mov_b32_e32 v25, v129
	v_mov_b32_e32 v26, v129
	v_mov_b32_e32 v27, v129
	v_mov_b32_e32 v28, v129
	v_mov_b32_e32 v29, v129
	v_mov_b32_e32 v30, v129
	v_mov_b32_e32 v31, v129
	v_mov_b32_e32 v64, 0
	v_mov_b32_e32 v65, v129
	v_mov_b32_e32 v66, v129
	v_mov_b32_e32 v67, v129
	v_mov_b32_e32 v68, v129
	v_mov_b32_e32 v69, v129
	v_mov_b32_e32 v70, v129
	v_mov_b32_e32 v71, v129
	v_mov_b32_e32 v72, v129
	v_mov_b32_e32 v73, v129
	v_mov_b32_e32 v74, v129
	v_mov_b32_e32 v75, v129
	v_mov_b32_e32 v76, v129
	v_mov_b32_e32 v77, v129
	v_mov_b32_e32 v78, v129
	v_mov_b32_e32 v79, v129
	v_mov_b32_e32 v80, 0
	v_mov_b32_e32 v81, v129
	v_mov_b32_e32 v82, v129
	v_mov_b32_e32 v83, v129
	v_mov_b32_e32 v84, v129
	v_mov_b32_e32 v85, v129
	v_mov_b32_e32 v86, v129
	v_mov_b32_e32 v87, v129
	v_mov_b32_e32 v88, v129
	v_mov_b32_e32 v89, v129
	v_mov_b32_e32 v90, v129
	v_mov_b32_e32 v91, v129
	v_mov_b32_e32 v92, v129
	v_mov_b32_e32 v93, v129
	v_mov_b32_e32 v94, v129
	v_mov_b32_e32 v95, v129
	v_mov_b32_e32 v32, 0
	v_mov_b32_e32 v33, v129
	v_mov_b32_e32 v34, v129
	v_mov_b32_e32 v35, v129
	v_mov_b32_e32 v36, v129
	v_mov_b32_e32 v37, v129
	v_mov_b32_e32 v38, v129
	v_mov_b32_e32 v39, v129
	v_mov_b32_e32 v40, v129
	v_mov_b32_e32 v41, v129
	v_mov_b32_e32 v42, v129
	v_mov_b32_e32 v43, v129
	v_mov_b32_e32 v44, v129
	v_mov_b32_e32 v45, v129
	v_mov_b32_e32 v46, v129
	v_mov_b32_e32 v47, v129
	v_mov_b32_e32 v48, 0
	v_mov_b32_e32 v49, v129
	v_mov_b32_e32 v50, v129
	v_mov_b32_e32 v51, v129
	v_mov_b32_e32 v52, v129
	v_mov_b32_e32 v53, v129
	v_mov_b32_e32 v54, v129
	v_mov_b32_e32 v55, v129
	v_mov_b32_e32 v56, v129
	v_mov_b32_e32 v57, v129
	v_mov_b32_e32 v58, v129
	v_mov_b32_e32 v59, v129
	v_mov_b32_e32 v60, v129
	v_mov_b32_e32 v61, v129
	v_mov_b32_e32 v62, v129
	v_mov_b32_e32 v63, v129
	v_mov_b32_e32 v96, 0
	v_mov_b32_e32 v97, v129
	v_mov_b32_e32 v98, v129
	v_mov_b32_e32 v99, v129
	v_mov_b32_e32 v100, v129
	v_mov_b32_e32 v101, v129
	v_mov_b32_e32 v102, v129
	v_mov_b32_e32 v103, v129
	v_mov_b32_e32 v104, v129
	v_mov_b32_e32 v105, v129
	v_mov_b32_e32 v106, v129
	v_mov_b32_e32 v107, v129
	v_mov_b32_e32 v108, v129
	v_mov_b32_e32 v109, v129
	v_mov_b32_e32 v110, v129
	v_mov_b32_e32 v111, v129
	v_mov_b32_e32 v112, 0
	v_mov_b32_e32 v113, v129
	v_mov_b32_e32 v114, v129
	v_mov_b32_e32 v115, v129
	v_mov_b32_e32 v116, v129
	v_mov_b32_e32 v117, v129
	v_mov_b32_e32 v118, v129
	v_mov_b32_e32 v119, v129
	v_readfirstlane_b32 s99, v165
	v_mov_b32_e32 v120, v129
	v_mov_b32_e32 v121, v129
	v_mov_b32_e32 v122, v129
	v_mov_b32_e32 v123, v129
	v_mov_b32_e32 v124, v129
	v_mov_b32_e32 v125, v129
	v_mov_b32_e32 v126, v129
	v_mov_b32_e32 v127, v129
